# in-proj panel 15 (8 real columns): MFMA blocks with all-zero B fragments skipped
# speedup vs baseline: 1.0070x; 1.0070x over previous
.LBB0_259:
	v_readfirstlane_b32 s100, v184
	s_nop 3
	s_lshr_b32 s100, s100, 6
	s_and_b32 s100, s100, 3
	s_cmp_eq_u32 s49, 15
	s_cselect_b32 s101, 1, 0
	s_cselect_b32 s100, s100, 0
	s_add_i32 s48, s48, 1
	s_mul_i32 s2, s48, s92
	s_mul_hi_u32 s3, s48, s60
	s_add_i32 s3, s3, s2
	s_mul_i32 s2, s48, s60
	s_add_u32 s26, s2, s90
	s_addc_u32 s27, s3, s66
	v_cmp_gt_i64_e32 vcc, s[26:27], v[196:197]
	v_cmp_lt_i64_e64 s[40:41], s[26:27], v[194:195]
	s_cbranch_vccnz .LBB0_265
	s_ashr_i32 s2, s26, 31
	s_lshr_b32 s2, s2, 29
	s_add_i32 s24, s26, s2
	s_and_b32 s2, s24, -8
	s_sub_i32 s25, s26, s2
	s_cmp_gt_i32 s25, -1
	s_mov_b64 s[22:23], -1
	s_cbranch_scc0 .LBB0_262
	s_lshl_b32 s26, s25, 7
	s_mov_b64 s[22:23], 0

.LBB0_266:
	s_add_u32 s2, s30, 0xfffc0080
	s_addc_u32 s3, s31, -1
	s_add_i32 s68, 0, 0x10000
	s_cmp_eq_u32 s47, 12
	s_cselect_b32 s37, s25, s3
	s_cselect_b32 s36, s43, s2
	s_cselect_b32 s35, s23, s46
	s_cselect_b32 s34, s44, s45
	s_add_i32 s2, 0, 0x14000
	v_add_u32_e32 v160, s68, v177
	v_add_u32_e32 v176, s2, v177
	ds_read_b128 v[128:131], v160
	ds_read_b128 v[132:135], v160 offset:1024
	ds_read_b128 v[156:159], v160 offset:2048
	ds_read_b128 v[160:163], v160 offset:3072
	ds_read_b128 v[164:167], v176
	ds_read_b128 v[168:171], v176 offset:1024
	ds_read_b128 v[172:175], v176 offset:2048
	ds_read_b128 v[178:181], v176 offset:3072
	v_lshl_add_u64 v[182:183], s[30:31], 0, v[152:153]
	s_add_i32 m0, s14, 0xc000
	ds_read_b128 v[202:205], v216
	ds_read_b128 v[206:209], v216 offset:1024
	ds_read_b128 v[210:213], v216 offset:2048
	ds_read_b128 v[218:221], v216 offset:3072
	ds_read_b128 v[230:233], v216 offset:4096
	ds_read_b128 v[238:241], v216 offset:5120
	ds_read_b128 v[242:245], v216 offset:6144
	ds_read_b128 v[246:249], v216 offset:7168
	global_load_lds_dwordx4 v[182:183], off
	v_lshl_add_u64 v[182:183], s[30:31], 0, v[154:155]
	s_add_i32 m0, s14, 0xe000
	s_nop 0
	global_load_lds_dwordx4 v[182:183], off
	s_waitcnt vmcnt(8)
	s_waitcnt lgkmcnt(0)
	s_barrier
	s_setprio 1
	s_cmp_lg_u32 s100, 0
	s_cbranch_scc1 .Ltskip_0
	s_waitcnt lgkmcnt(0)
	v_mfma_f32_16x16x32_bf16 v[60:63], v[128:131], v[202:205], v[60:63]
	v_mfma_f32_16x16x32_bf16 v[56:59], v[156:159], v[202:205], v[56:59]
	v_mfma_f32_16x16x32_bf16 v[52:55], v[128:131], v[210:213], v[52:55]
	v_mfma_f32_16x16x32_bf16 v[48:51], v[156:159], v[210:213], v[48:51]
	v_mfma_f32_16x16x32_bf16 v[44:47], v[128:131], v[230:233], v[44:47]
	v_mfma_f32_16x16x32_bf16 v[40:43], v[156:159], v[230:233], v[40:43]
	v_mfma_f32_16x16x32_bf16 v[36:39], v[128:131], v[242:245], v[36:39]
	v_mfma_f32_16x16x32_bf16 v[32:35], v[156:159], v[242:245], v[32:35]
	v_mfma_f32_16x16x32_bf16 v[60:63], v[132:135], v[206:209], v[60:63]
	v_mfma_f32_16x16x32_bf16 v[56:59], v[160:163], v[206:209], v[56:59]
	v_mfma_f32_16x16x32_bf16 v[52:55], v[132:135], v[218:221], v[52:55]
	v_mfma_f32_16x16x32_bf16 v[48:51], v[160:163], v[218:221], v[48:51]
	v_mfma_f32_16x16x32_bf16 v[44:47], v[132:135], v[238:241], v[44:47]
	v_mfma_f32_16x16x32_bf16 v[40:43], v[160:163], v[238:241], v[40:43]
	v_mfma_f32_16x16x32_bf16 v[36:39], v[132:135], v[246:249], v[36:39]
	v_mfma_f32_16x16x32_bf16 v[32:35], v[160:163], v[246:249], v[32:35]
.Ltskip_0:
	s_setprio 0
	s_setprio 1
	s_cmp_lg_u32 s101, 0
	s_cbranch_scc1 .Ltskip_1
	v_mfma_f32_16x16x32_bf16 v[124:127], v[164:167], v[202:205], v[124:127]
	v_mfma_f32_16x16x32_bf16 v[120:123], v[172:175], v[202:205], v[120:123]
	v_mfma_f32_16x16x32_bf16 v[116:119], v[164:167], v[210:213], v[116:119]
	v_mfma_f32_16x16x32_bf16 v[112:115], v[172:175], v[210:213], v[112:115]
	v_mfma_f32_16x16x32_bf16 v[108:111], v[164:167], v[230:233], v[108:111]
	v_mfma_f32_16x16x32_bf16 v[104:107], v[172:175], v[230:233], v[104:107]
	v_mfma_f32_16x16x32_bf16 v[100:103], v[164:167], v[242:245], v[100:103]
	v_mfma_f32_16x16x32_bf16 v[96:99], v[172:175], v[242:245], v[96:99]
	v_mfma_f32_16x16x32_bf16 v[124:127], v[168:171], v[206:209], v[124:127]
	v_mfma_f32_16x16x32_bf16 v[120:123], v[178:181], v[206:209], v[120:123]
	v_mfma_f32_16x16x32_bf16 v[116:119], v[168:171], v[218:221], v[116:119]
	v_mfma_f32_16x16x32_bf16 v[112:115], v[178:181], v[218:221], v[112:115]
	v_mfma_f32_16x16x32_bf16 v[108:111], v[168:171], v[238:241], v[108:111]
	v_mfma_f32_16x16x32_bf16 v[104:107], v[178:181], v[238:241], v[104:107]
	v_mfma_f32_16x16x32_bf16 v[100:103], v[168:171], v[246:249], v[100:103]
	v_mfma_f32_16x16x32_bf16 v[96:99], v[178:181], v[246:249], v[96:99]
.Ltskip_1:
	s_setprio 0
	s_barrier
	s_add_i32 s3, s68, s13
	v_lshl_add_u64 v[182:183], s[34:35], 0, v[140:141]
	s_mov_b32 m0, s3
	ds_read_b128 v[202:205], v216 offset:16384
	ds_read_b128 v[206:209], v216 offset:17408
	ds_read_b128 v[210:213], v216 offset:18432
	ds_read_b128 v[218:221], v216 offset:19456
	ds_read_b128 v[230:233], v216 offset:20480
	ds_read_b128 v[238:241], v216 offset:21504
	ds_read_b128 v[242:245], v216 offset:22528
	ds_read_b128 v[246:249], v216 offset:23552
	global_load_lds_dwordx4 v[182:183], off
	s_add_i32 m0, s3, 0x2000
	s_add_u32 s68, s34, 0x40000
	v_lshl_add_u64 v[214:215], s[34:35], 0, v[136:137]
	s_addc_u32 s69, s35, 0
	s_add_i32 s2, s2, s13
	global_load_lds_dwordx4 v[214:215], off
	v_lshl_add_u64 v[222:223], s[68:69], 0, v[140:141]
	s_mov_b32 m0, s2
	v_lshl_add_u64 v[234:235], s[36:37], 0, v[138:139]
	global_load_lds_dwordx4 v[222:223], off
	v_lshl_add_u64 v[222:223], s[68:69], 0, v[136:137]
	s_add_i32 m0, s2, 0x2000
	s_nop 0
	global_load_lds_dwordx4 v[222:223], off
	v_lshl_add_u64 v[222:223], s[36:37], 0, v[142:143]
	s_mov_b32 m0, s14
	s_nop 0
	global_load_lds_dwordx4 v[222:223], off
	s_mov_b32 m0, s15
	s_nop 0
	global_load_lds_dwordx4 v[234:235], off
	s_waitcnt vmcnt(8)
	s_waitcnt lgkmcnt(0)
	s_barrier
	s_setprio 1
	s_cmp_lg_u32 s100, 0
	s_cbranch_scc1 .Ltskip_2
	s_waitcnt lgkmcnt(0)
	v_mfma_f32_16x16x32_bf16 v[28:31], v[128:131], v[202:205], v[28:31]
	v_mfma_f32_16x16x32_bf16 v[24:27], v[156:159], v[202:205], v[24:27]
	v_mfma_f32_16x16x32_bf16 v[20:23], v[128:131], v[210:213], v[20:23]
	v_mfma_f32_16x16x32_bf16 v[16:19], v[156:159], v[210:213], v[16:19]
	v_mfma_f32_16x16x32_bf16 v[12:15], v[128:131], v[230:233], v[12:15]
	v_mfma_f32_16x16x32_bf16 v[8:11], v[156:159], v[230:233], v[8:11]
	v_mfma_f32_16x16x32_bf16 v[4:7], v[128:131], v[242:245], v[4:7]
	v_mfma_f32_16x16x32_bf16 v[0:3], v[156:159], v[242:245], v[0:3]
	v_mfma_f32_16x16x32_bf16 v[28:31], v[132:135], v[206:209], v[28:31]
	v_mfma_f32_16x16x32_bf16 v[24:27], v[160:163], v[206:209], v[24:27]
	v_mfma_f32_16x16x32_bf16 v[20:23], v[132:135], v[218:221], v[20:23]
	v_mfma_f32_16x16x32_bf16 v[16:19], v[160:163], v[218:221], v[16:19]
	v_mfma_f32_16x16x32_bf16 v[12:15], v[132:135], v[238:241], v[12:15]
	v_mfma_f32_16x16x32_bf16 v[8:11], v[160:163], v[238:241], v[8:11]
	v_mfma_f32_16x16x32_bf16 v[4:7], v[132:135], v[246:249], v[4:7]
	v_mfma_f32_16x16x32_bf16 v[0:3], v[160:163], v[246:249], v[0:3]
.Ltskip_2:
	s_setprio 0
	s_setprio 1
	s_cmp_lg_u32 s101, 0
	s_cbranch_scc1 .Ltskip_3
	v_mfma_f32_16x16x32_bf16 v[92:95], v[164:167], v[202:205], v[92:95]
	v_mfma_f32_16x16x32_bf16 v[88:91], v[172:175], v[202:205], v[88:91]
	v_mfma_f32_16x16x32_bf16 v[84:87], v[164:167], v[210:213], v[84:87]
	v_mfma_f32_16x16x32_bf16 v[80:83], v[172:175], v[210:213], v[80:83]
	v_mfma_f32_16x16x32_bf16 v[76:79], v[164:167], v[230:233], v[76:79]
	v_mfma_f32_16x16x32_bf16 v[72:75], v[172:175], v[230:233], v[72:75]
	v_mfma_f32_16x16x32_bf16 v[68:71], v[164:167], v[242:245], v[68:71]
	v_mfma_f32_16x16x32_bf16 v[64:67], v[172:175], v[242:245], v[64:67]
	v_mfma_f32_16x16x32_bf16 v[92:95], v[168:171], v[206:209], v[92:95]
	v_mfma_f32_16x16x32_bf16 v[88:91], v[178:181], v[206:209], v[88:91]
	v_mfma_f32_16x16x32_bf16 v[84:87], v[168:171], v[218:221], v[84:87]
	v_mfma_f32_16x16x32_bf16 v[80:83], v[178:181], v[218:221], v[80:83]
	v_mfma_f32_16x16x32_bf16 v[76:79], v[168:171], v[238:241], v[76:79]
	v_mfma_f32_16x16x32_bf16 v[72:75], v[178:181], v[238:241], v[72:75]
	v_mfma_f32_16x16x32_bf16 v[68:71], v[168:171], v[246:249], v[68:71]
	v_mfma_f32_16x16x32_bf16 v[64:67], v[178:181], v[246:249], v[64:67]
.Ltskip_3:
	s_setprio 0
	s_barrier
	s_add_i32 s2, 0, 0x18000
	s_add_i32 s3, 0, 0x1c000
	v_add_u32_e32 v160, s2, v177
	v_add_u32_e32 v176, s3, v177
	ds_read_b128 v[128:131], v160
	ds_read_b128 v[132:135], v160 offset:1024
	ds_read_b128 v[156:159], v160 offset:2048
	ds_read_b128 v[160:163], v160 offset:3072
	ds_read_b128 v[164:167], v176
	ds_read_b128 v[168:171], v176 offset:1024
	ds_read_b128 v[172:175], v176 offset:2048
	ds_read_b128 v[178:181], v176 offset:3072
	s_add_u32 s36, s36, 0x40000
	s_addc_u32 s37, s37, 0
	s_mov_b32 m0, s10
	v_lshl_add_u64 v[250:251], s[36:37], 0, v[142:143]
	ds_read_b128 v[202:205], v216 offset:32768
	ds_read_b128 v[206:209], v216 offset:33792
	ds_read_b128 v[210:213], v216 offset:34816
	ds_read_b128 v[218:221], v216 offset:35840
	ds_read_b128 v[230:233], v216 offset:36864
	ds_read_b128 v[238:241], v216 offset:37888
	ds_read_b128 v[242:245], v216 offset:38912
	ds_read_b128 v[246:249], v216 offset:39936
	global_load_lds_dwordx4 v[250:251], off
	v_lshl_add_u64 v[250:251], s[36:37], 0, v[138:139]
	s_mov_b32 m0, s11
	s_nop 0
	global_load_lds_dwordx4 v[250:251], off
	s_waitcnt vmcnt(8)
	s_waitcnt lgkmcnt(0)
	s_barrier
	s_setprio 1
	s_cmp_lg_u32 s100, 0
	s_cbranch_scc1 .Ltskip_4
	s_waitcnt lgkmcnt(0)
	v_mfma_f32_16x16x32_bf16 v[60:63], v[128:131], v[202:205], v[60:63]
	v_mfma_f32_16x16x32_bf16 v[56:59], v[156:159], v[202:205], v[56:59]
	v_mfma_f32_16x16x32_bf16 v[52:55], v[128:131], v[210:213], v[52:55]
	v_mfma_f32_16x16x32_bf16 v[48:51], v[156:159], v[210:213], v[48:51]
	v_mfma_f32_16x16x32_bf16 v[44:47], v[128:131], v[230:233], v[44:47]
	v_mfma_f32_16x16x32_bf16 v[40:43], v[156:159], v[230:233], v[40:43]
	v_mfma_f32_16x16x32_bf16 v[36:39], v[128:131], v[242:245], v[36:39]
	v_mfma_f32_16x16x32_bf16 v[32:35], v[156:159], v[242:245], v[32:35]
	v_mfma_f32_16x16x32_bf16 v[60:63], v[132:135], v[206:209], v[60:63]
	v_mfma_f32_16x16x32_bf16 v[56:59], v[160:163], v[206:209], v[56:59]
	v_mfma_f32_16x16x32_bf16 v[52:55], v[132:135], v[218:221], v[52:55]
	v_mfma_f32_16x16x32_bf16 v[48:51], v[160:163], v[218:221], v[48:51]
	v_mfma_f32_16x16x32_bf16 v[44:47], v[132:135], v[238:241], v[44:47]
	v_mfma_f32_16x16x32_bf16 v[40:43], v[160:163], v[238:241], v[40:43]
	v_mfma_f32_16x16x32_bf16 v[36:39], v[132:135], v[246:249], v[36:39]
	v_mfma_f32_16x16x32_bf16 v[32:35], v[160:163], v[246:249], v[32:35]

.Ltskip_5:
	s_setprio 0
	s_barrier
	s_add_i32 s2, s2, s13
	v_lshl_add_u64 v[182:183], v[182:183], 0, s[84:85]
	s_mov_b32 m0, s2
	ds_read_b128 v[202:205], v216 offset:49152
	ds_read_b128 v[206:209], v216 offset:50176
	ds_read_b128 v[210:213], v216 offset:51200
	ds_read_b128 v[218:221], v216 offset:52224
	ds_read_b128 v[230:233], v216 offset:53248
	ds_read_b128 v[238:241], v216 offset:54272
	ds_read_b128 v[242:245], v216 offset:55296
	ds_read_b128 v[246:249], v216 offset:56320
	global_load_lds_dwordx4 v[182:183], off
	s_add_i32 m0, s2, 0x2000
	s_add_u32 s34, s34, 0x40080
	v_lshl_add_u64 v[182:183], v[214:215], 0, s[84:85]
	s_addc_u32 s35, s35, 0
	s_add_i32 s2, s3, s13
	global_load_lds_dwordx4 v[182:183], off
	v_lshl_add_u64 v[182:183], s[34:35], 0, v[140:141]
	s_mov_b32 m0, s2
	s_nop 0
	global_load_lds_dwordx4 v[182:183], off
	v_lshl_add_u64 v[182:183], s[34:35], 0, v[136:137]
	s_add_i32 m0, s2, 0x2000
	s_nop 0
	global_load_lds_dwordx4 v[182:183], off
	v_lshl_add_u64 v[182:183], v[222:223], 0, s[84:85]
	s_mov_b32 m0, s18
	s_nop 0
	global_load_lds_dwordx4 v[182:183], off
	v_lshl_add_u64 v[182:183], v[234:235], 0, s[84:85]
	s_mov_b32 m0, s19
	s_nop 0
	global_load_lds_dwordx4 v[182:183], off
	s_waitcnt vmcnt(8)
	s_waitcnt lgkmcnt(0)
	s_barrier
	s_setprio 1
	s_cmp_lg_u32 s100, 0
	s_cbranch_scc1 .Ltskip_6
	s_waitcnt lgkmcnt(0)
	v_mfma_f32_16x16x32_bf16 v[28:31], v[128:131], v[202:205], v[28:31]
	v_mfma_f32_16x16x32_bf16 v[24:27], v[156:159], v[202:205], v[24:27]
	v_mfma_f32_16x16x32_bf16 v[20:23], v[128:131], v[210:213], v[20:23]
	v_mfma_f32_16x16x32_bf16 v[16:19], v[156:159], v[210:213], v[16:19]
	v_mfma_f32_16x16x32_bf16 v[12:15], v[128:131], v[230:233], v[12:15]
	v_mfma_f32_16x16x32_bf16 v[8:11], v[156:159], v[230:233], v[8:11]
	v_mfma_f32_16x16x32_bf16 v[4:7], v[128:131], v[242:245], v[4:7]
	v_mfma_f32_16x16x32_bf16 v[0:3], v[156:159], v[242:245], v[0:3]
	v_mfma_f32_16x16x32_bf16 v[28:31], v[132:135], v[206:209], v[28:31]
	v_mfma_f32_16x16x32_bf16 v[24:27], v[160:163], v[206:209], v[24:27]
	v_mfma_f32_16x16x32_bf16 v[20:23], v[132:135], v[218:221], v[20:23]
	v_mfma_f32_16x16x32_bf16 v[16:19], v[160:163], v[218:221], v[16:19]
	v_mfma_f32_16x16x32_bf16 v[12:15], v[132:135], v[238:241], v[12:15]
	v_mfma_f32_16x16x32_bf16 v[8:11], v[160:163], v[238:241], v[8:11]
	v_mfma_f32_16x16x32_bf16 v[4:7], v[132:135], v[246:249], v[4:7]
	v_mfma_f32_16x16x32_bf16 v[0:3], v[160:163], v[246:249], v[0:3]

.Ltskip_7:
	s_setprio 0
	s_barrier
	s_add_i32 s47, s47, 2
	s_add_u32 s30, s30, 0x100
	s_addc_u32 s31, s31, 0
	s_add_u32 s45, s45, 0x100
	s_addc_u32 s46, s46, 0
	s_cmp_gt_u32 s47, 13
	s_cbranch_scc0 .LBB0_266
	s_and_b64 vcc, exec, s[20:21]
	s_cbranch_vccz .LBB0_269
	s_barrier
